# head-loop back-edge: the A3c closing barrier is kept only on the loop exit (the next head's loop-top barrier already orders the LDS reuse); on top of all18
# baseline (speedup 1.0000x reference)
; #define LAS __attribute__((address_space(3)))
; __device__ __forceinline__ void st4_lds(LAS unsigned char* p, f32x4 v) { v2u w; w.x = pk2(v[0], v[1]); w.y = pk2(v[2], v[3]); *(LAS v2u*)p = w; }
; __device__ __forceinline__ void st4_g(bf16* p, f32x4 v) { v2u w; w.x = pk2(v[0], v[1]); w.y = pk2(v[2], v[3]); *(GAS v2u*)p = w; }
; __device__ __forceinline__ f32x4 ld4_lds(const LAS unsigned char* p) { const v2u w = *(const LAS v2u*)p; return (f32x4){bflo(w.x), bfhi(w.x), bflo(w.y), bfhi(w.y)}; }
; #define LBAR() asm volatile("s_waitcnt lgkmcnt(0)\n\ts_barrier" ::: "memory")
; __device__ __forceinline__ void rwkv_chunk_group(Frame& F, int bc, unsigned long long& tsub) {
;     ...
; #pragma unroll
;     for (int q = 0; q < 2; ++q) { const int tw = 2 * w + q, p0 = 16 * (tw >> 2), q0 = 16 * (tw & 3); const int o = (p0 + fr) * LD + (q0 + 4 * fq) * 2;
;         const f32x4 ap = mm_tile(L + L_TT, LD, q0, L + L_ATT, LD, p0, 2, Z4, fr, fq);
;         const f32x4 w1 = mm_tile(L + L_NAK, LD, q0, L + L_VT, LD, p0, 2, Z4, fr, fq);
;         st4_lds(L + L_APT + o, ap); st4_lds(L + L_W1T + o, w1); }
;     LBAR();
;     {
;         bf16* RPp = (bf16*)(F.ws + WS_RP) + (size_t)item * 4096; bf16* PTp = (bf16*)(F.ws + WS_PT) + (size_t)item * 4096;
; #pragma unroll
;         for (int q = 0; q < 2; ++q) { const int tw = 2 * w + q, p0 = 16 * (tw >> 2), q0 = 16 * (tw & 3); const int p = p0 + fr; const int o = p * LD + (q0 + 4 * fq) * 2;
;             const f32x4 u0 = mm_tile(L + L_TT, LD, q0, L + L_W1T, LD, p0, 2, Z4, fr, fq);
;             const f32x4 rp = mm_tile(L + L_APT, LD, q0, L + L_NRB, LD, p0, 2, ld4_lds(L + L_RT + o), fr, fq);
;             f32x4 pt = mm_tile(L + L_APT, LD, q0, L + L_BH, LD, p0, 2, Z4, fr, fq);
;             const float wc = *(const LAS float*)(L + L_WC + p * 4);
; #pragma unroll
;             for (int v = 0; v < 4; ++v) if (p == q0 + 4 * fq + v) pt[v] += wc;
;             st4_lds(L + L_U0T + o, u0);
;             st4_g(RPp + p * 64 + q0 + 4 * fq, rp); st4_g(PTp + ((p0 >> 4) * 2 + (q0 >> 5)) * 512 + fr * 32 + (q0 & 16) + 4 * fq, pt); }
.LBB0_1411:
	v_add_u32_e32 v130, v108, v110
	v_add_u32_e32 v131, v108, v128
	v_add_u32_e32 v133, v109, v110
	v_add_u32_e32 v148, v109, v128
	s_lshl_b64 s[64:65], s[72:73], 1
	s_mov_b32 s77, s95
	s_mov_b32 s93, s95
	ds_read_b128 v[174:177], v130
	ds_read_b128 v[80:83], v107 offset:36864
	ds_read_b128 v[88:91], v133
	ds_read_b128 v[190:193], v107 offset:46080
	ds_read_b128 v[182:185], v131
	ds_read_b128 v[96:99], v148
	ds_read_b128 v[178:181], v130 offset:64
	ds_read_b128 v[84:87], v107 offset:36928
	ds_read_b128 v[92:95], v133 offset:64
	ds_read_b128 v[194:197], v107 offset:46144
	ds_read_b128 v[186:189], v131 offset:64
	ds_read_b128 v[100:103], v148 offset:64
	s_waitcnt lgkmcnt(10)
	v_mfma_f32_16x16x32_bf16 v[36:39], v[174:177], v[80:83], 0
	s_waitcnt lgkmcnt(8)
	v_mfma_f32_16x16x32_bf16 v[40:43], v[88:91], v[190:193], 0
	s_waitcnt lgkmcnt(7)
	v_mfma_f32_16x16x32_bf16 v[44:47], v[182:185], v[80:83], 0
	s_waitcnt lgkmcnt(6)
	v_mfma_f32_16x16x32_bf16 v[224:227], v[96:99], v[190:193], 0
	s_waitcnt lgkmcnt(4)
	v_mfma_f32_16x16x32_bf16 v[36:39], v[178:181], v[84:87], v[36:39]
	s_waitcnt lgkmcnt(2)
	v_mfma_f32_16x16x32_bf16 v[40:43], v[92:95], v[194:197], v[40:43]
	s_waitcnt lgkmcnt(1)
	v_mfma_f32_16x16x32_bf16 v[44:47], v[186:189], v[84:87], v[44:47]
	s_waitcnt lgkmcnt(0)
	v_mfma_f32_16x16x32_bf16 v[224:227], v[100:103], v[194:197], v[224:227]
	ds_read_b128 v[228:231], v144
	ds_read_b128 v[232:235], v144 offset:64
	ds_read_b64 v[250:251], v78 offset:27648
	ds_read_b64 v[164:165], v79 offset:27648
	ds_read_b32 v173, v145
	s_nop 7
	v_cvt_pk_bf16_f32 v36, v36, v37
	v_cvt_pk_bf16_f32 v37, v38, v39
	v_cvt_pk_bf16_f32 v38, v40, v41
	v_cvt_pk_bf16_f32 v39, v42, v43
	ds_write2st64_b64 v142, v[36:37], v[38:39] offset1:18
	v_cvt_pk_bf16_f32 v44, v44, v45
	v_cvt_pk_bf16_f32 v45, v46, v47
	v_cvt_pk_bf16_f32 v46, v224, v225
	v_cvt_pk_bf16_f32 v47, v226, v227
	ds_write2st64_b64 v143, v[44:45], v[46:47] offset1:18
	ds_read_b128 v[80:83], v107 offset:55296
	ds_read_b128 v[84:87], v107 offset:55360
	s_waitcnt lgkmcnt(0)
	s_barrier
	ds_read_b128 v[88:91], v107 offset:9216
	ds_read_b128 v[96:99], v76
	ds_read_b128 v[236:239], v77
	ds_read_b128 v[92:95], v107 offset:9280
	ds_read_b128 v[100:103], v76 offset:64
	ds_read_b128 v[242:245], v77 offset:64
	v_lshlrev_b32_e32 v40, 16, v250
	v_and_b32_e32 v41, 0xffff0000, v250
	v_lshlrev_b32_e32 v42, 16, v251
	v_and_b32_e32 v43, 0xffff0000, v251
	v_lshlrev_b32_e32 v246, 16, v164
	v_and_b32_e32 v247, 0xffff0000, v164
	v_lshlrev_b32_e32 v248, 16, v165
	v_and_b32_e32 v249, 0xffff0000, v165
	s_waitcnt lgkmcnt(5)
	v_mfma_f32_16x16x32_bf16 v[36:39], v[174:177], v[88:91], 0
	s_waitcnt lgkmcnt(4)
	v_mfma_f32_16x16x32_bf16 v[40:43], v[96:99], v[228:231], v[40:43]
	v_mfma_f32_16x16x32_bf16 v[44:47], v[96:99], v[80:83], 0
	v_mfma_f32_16x16x32_bf16 v[224:227], v[182:185], v[88:91], 0
	s_waitcnt lgkmcnt(3)
	v_mfma_f32_16x16x32_bf16 v[246:249], v[236:239], v[228:231], v[246:249]
	v_mfma_f32_16x16x32_bf16 v[198:201], v[236:239], v[80:83], 0
	s_waitcnt lgkmcnt(2)
	v_mfma_f32_16x16x32_bf16 v[36:39], v[178:181], v[92:95], v[36:39]
	s_waitcnt lgkmcnt(1)
	v_mfma_f32_16x16x32_bf16 v[40:43], v[100:103], v[232:235], v[40:43]
	v_mfma_f32_16x16x32_bf16 v[44:47], v[100:103], v[84:87], v[44:47]
	v_mfma_f32_16x16x32_bf16 v[224:227], v[186:189], v[92:95], v[224:227]
	s_waitcnt lgkmcnt(0)
	v_mfma_f32_16x16x32_bf16 v[246:249], v[242:245], v[232:235], v[246:249]
	v_mfma_f32_16x16x32_bf16 v[198:201], v[242:245], v[84:87], v[198:201]
	v_lshl_add_u64 v[148:149], v[66:67], 0, s[64:65]
	v_lshl_add_u64 v[150:151], v[74:75], 0, s[64:65]
	v_lshl_add_u64 v[160:161], v[68:69], 0, s[64:65]
	v_lshl_add_u64 v[166:167], v[70:71], 0, s[64:65]
	s_nop 4
	v_cvt_pk_bf16_f32 v36, v36, v37
	v_cvt_pk_bf16_f32 v37, v38, v39
	ds_write_b64 v78, v[36:37] offset:18432
	v_cvt_pk_bf16_f32 v224, v224, v225
	v_cvt_pk_bf16_f32 v225, v226, v227
	ds_write_b64 v79, v[224:225] offset:18432
	ds_read_b128 v[80:83], v146
	ds_read_b128 v[84:87], v146 offset:64
	ds_read_b128 v[96:99], v76 offset:46080
	ds_read_b128 v[174:177], v76 offset:64512
	ds_read_b128 v[182:185], v76 offset:55296
	ds_read_b128 v[100:103], v76 offset:46144
	ds_read_b128 v[178:181], v76 offset:64576
	ds_read_b128 v[186:189], v76 offset:55360
	v_add_f32_e32 v168, v173, v44
	v_cndmask_b32_e64 v44, v44, v168, s[18:19]
	v_add_f32_e32 v168, v173, v45
	v_cndmask_b32_e64 v45, v45, v168, s[20:21]
	v_add_f32_e32 v168, v173, v46
	v_cndmask_b32_e64 v46, v46, v168, s[22:23]
	v_add_f32_e32 v168, v173, v47
	v_cndmask_b32_e64 v47, v47, v168, s[24:25]
	v_add_f32_e32 v168, v173, v198
	v_cndmask_b32_e64 v198, v198, v168, s[26:27]
	v_add_f32_e32 v168, v173, v199
	v_cndmask_b32_e64 v199, v199, v168, s[28:29]
	v_add_f32_e32 v168, v173, v200
	v_cndmask_b32_e64 v200, v200, v168, s[30:31]
	v_add_f32_e32 v168, v173, v201
	v_cndmask_b32_e64 v201, v201, v168, s[34:35]
	v_cvt_pk_bf16_f32 v40, v40, v41
	v_cvt_pk_bf16_f32 v41, v42, v43
	v_lshl_add_u64 v[168:169], v[148:149], 0, s[76:77]
	global_store_dwordx2 v[168:169], v[40:41], off
	v_cvt_pk_bf16_f32 v44, v44, v45
	v_cvt_pk_bf16_f32 v45, v46, v47
	global_store_dwordx2 v[150:151], v[44:45], off
	v_cvt_pk_bf16_f32 v246, v246, v247
	v_cvt_pk_bf16_f32 v247, v248, v249
	v_lshl_add_u64 v[168:169], v[148:149], 0, s[92:93]
	global_store_dwordx2 v[168:169], v[246:247], off
	v_cvt_pk_bf16_f32 v198, v198, v199
	v_cvt_pk_bf16_f32 v199, v200, v201
	global_store_dwordx2 v[150:151], v[198:199], off offset:32
	s_waitcnt lgkmcnt(0)
	s_barrier
; #define LAS __attribute__((address_space(3)))
; __device__ __forceinline__ void st4_g(bf16* p, f32x4 v) { v2u w; w.x = pk2(v[0], v[1]); w.y = pk2(v[2], v[3]); *(GAS v2u*)p = w; }
; #define LBAR() asm volatile("s_waitcnt lgkmcnt(0)\n\ts_barrier" ::: "memory")
; __device__ __forceinline__ void rwkv_chunk_group(Frame& F, int bc, unsigned long long& tsub) {
;     ...
;         asm volatile("s_waitcnt vmcnt(0)" ::: "memory"); LBAR();
;         f32x4 aw[2], aa[2], ag[2];
; #pragma unroll
;         for (int q = 0; q < 2; ++q) { const int n0 = 16 * ((2 * w + q) & 3); aw[q] = Z4; aa[q] = Z4; ag[q] = Z4;
;             const LAS unsigned char* wp = L + L_LWA + (n0 + fr) * 128 + fq * 16; const LAS unsigned char* gp = L + L_LG + (n0 + fr) * 64 + fq * 16;
; #pragma unroll
;             for (int k = 0; k < 2; ++k) { aw[q] = __builtin_amdgcn_mfma_f32_16x16x32_bf16(xw[k], *(const LAS bf16x8*)(wp + k * 64), aw[q], 0, 0, 0); aa[q] = __builtin_amdgcn_mfma_f32_16x16x32_bf16(xa[k], *(const LAS bf16x8*)(wp + 8192 + k * 64), aa[q], 0, 0, 0); }
;     ...
;     {
;         bf16* Y0p = (bf16*)(F.ws + WS_Y0) + (size_t)item * 4096; bf16* QCp = (bf16*)(F.ws + WS_QC) + (size_t)item * 4096;
; #pragma unroll
;         for (int q = 0; q < 2; ++q) { const int tw = 2 * w + q, p0 = 16 * (tw >> 2), q0 = 16 * (tw & 3); const int p = p0 + fr;
;             f32x4 y0 = mm_tile(L + L_VT, LD, q0, L + L_NRK, LD, p0, 2, Z4, fr, fq);
;             y0 = mm_tile(L + L_U0T, LD, q0, L + L_NRB, LD, p0, 2, y0, fr, fq);
;             f32x4 qc = mm_tile(L + L_KH, LD, q0, L + L_VT, LD, p0, 2, Z4, fr, fq);
;             qc = mm_tile(L + L_BH, LD, q0, L + L_U0T, LD, p0, 2, qc, fr, fq);
;             st4_g(Y0p + p * 64 + q0 + 4 * fq, y0); st4_g(QCp + p * 64 + q0 + 4 * fq, qc); }
;     }
;     LBAR();
	ds_read_b128 v[88:91], v107 offset:18432
	ds_read_b128 v[236:239], v76 offset:18432
	ds_read_b128 v[92:95], v107 offset:18496
	ds_read_b128 v[242:245], v76 offset:18496
	ds_read_b128 v[246:249], v77 offset:46080
	ds_read_b128 v[198:201], v77 offset:46144
	v_mfma_f32_16x16x32_bf16 v[36:39], v[96:99], v[80:83], 0
	v_mfma_f32_16x16x32_bf16 v[36:39], v[100:103], v[84:87], v[36:39]
	v_mfma_f32_16x16x32_bf16 v[40:43], v[174:177], v[190:193], 0
	v_mfma_f32_16x16x32_bf16 v[40:43], v[178:181], v[194:197], v[40:43]
	ds_read_b128 v[174:177], v77 offset:64512
	ds_read_b128 v[178:181], v77 offset:64576
	s_waitcnt lgkmcnt(7)
	v_mfma_f32_16x16x32_bf16 v[40:43], v[182:185], v[88:91], v[40:43]
	s_waitcnt lgkmcnt(5)
	v_mfma_f32_16x16x32_bf16 v[40:43], v[186:189], v[92:95], v[40:43]
	ds_read_b128 v[182:185], v77 offset:55296
	ds_read_b128 v[186:189], v77 offset:55360
	v_mfma_f32_16x16x32_bf16 v[36:39], v[236:239], v[228:231], v[36:39]
	s_waitcnt lgkmcnt(6)
	v_mfma_f32_16x16x32_bf16 v[36:39], v[242:245], v[232:235], v[36:39]
	ds_read_b128 v[236:239], v77 offset:18432
	ds_read_b128 v[242:245], v77 offset:18496
	s_waitcnt lgkmcnt(7)
	v_mfma_f32_16x16x32_bf16 v[44:47], v[246:249], v[80:83], 0
	s_waitcnt lgkmcnt(6)
	v_mfma_f32_16x16x32_bf16 v[44:47], v[198:201], v[84:87], v[44:47]
	s_waitcnt lgkmcnt(5)
	v_mfma_f32_16x16x32_bf16 v[224:227], v[174:177], v[190:193], 0
	s_waitcnt lgkmcnt(4)
	v_mfma_f32_16x16x32_bf16 v[224:227], v[178:181], v[194:197], v[224:227]
	s_waitcnt lgkmcnt(3)
	v_mfma_f32_16x16x32_bf16 v[224:227], v[182:185], v[88:91], v[224:227]
	s_waitcnt lgkmcnt(2)
	v_mfma_f32_16x16x32_bf16 v[224:227], v[186:189], v[92:95], v[224:227]
	s_waitcnt lgkmcnt(1)
	v_mfma_f32_16x16x32_bf16 v[44:47], v[236:239], v[228:231], v[44:47]
	s_waitcnt lgkmcnt(0)
	v_mfma_f32_16x16x32_bf16 v[44:47], v[242:245], v[232:235], v[44:47]
	v_cvt_pk_bf16_f32 v36, v36, v37
	v_cvt_pk_bf16_f32 v37, v38, v39
	v_lshl_add_u64 v[168:169], v[160:161], 0, s[76:77]
	global_store_dwordx2 v[168:169], v[36:37], off
	v_cvt_pk_bf16_f32 v40, v40, v41
	v_cvt_pk_bf16_f32 v41, v42, v43
	v_lshl_add_u64 v[168:169], v[166:167], 0, s[76:77]
	global_store_dwordx2 v[168:169], v[40:41], off
	s_nop 7
	v_cvt_pk_bf16_f32 v224, v224, v225
	v_cvt_pk_bf16_f32 v225, v226, v227
	v_lshl_add_u64 v[168:169], v[166:167], 0, s[92:93]
	global_store_dwordx2 v[168:169], v[224:225], off
	v_cvt_pk_bf16_f32 v44, v44, v45
	v_cvt_pk_bf16_f32 v45, v46, v47
	v_lshl_add_u64 v[168:169], v[160:161], 0, s[92:93]
	global_store_dwordx2 v[168:169], v[44:45], off
	s_waitcnt lgkmcnt(0)
	s_cmp_lg_u32 s12, 8
	s_cbranch_scc1 .La3_next
	s_barrier
	s_branch .LBB0_1392
.La3_next:
.LBB0_1412:
	s_waitcnt vmcnt(8)
	v_perm_b32 v160, v203, v202, s5
	v_perm_b32 v161, v216, v215, s5
	v_perm_b32 v166, v204, v203, s5
	v_perm_b32 v167, v217, v216, s5
	v_perm_b32 v168, v206, v205, s5
	v_perm_b32 v169, v219, v218, s5
	v_perm_b32 v170, v212, v207, s5
	v_perm_b32 v171, v221, v220, s5
	v_perm_b32 v165, v214, v213, s5
	v_perm_b32 v172, v223, v222, s5
	v_readlane_b32 s98, v254, 2
	v_readlane_b32 s100, v254, 20
	v_readlane_b32 s101, v254, 21
	s_add_i32 s98, s98, s12
	s_lshl_b32 s98, s98, 6
	s_and_b32 s98, s98, 0x1c0
	v_add_lshl_u32 v238, v208, s98, 2
	v_mov_b32_e32 v239, 0
	s_nop 0
	v_lshl_add_u64 v[232:233], s[100:101], 0, v[238:239]
	s_mov_b64 s[100:101], 0x2000
	v_lshl_add_u64 v[234:235], v[232:233], 0, s[100:101]
	s_mov_b64 s[100:101], 0x3800
	v_lshl_add_u64 v[236:237], v[232:233], 0, s[100:101]
	global_load_dword v224, v[232:233], off
	global_load_dword v225, v[232:233], off offset:2048
	global_load_dword v226, v[234:235], off offset:-4096
	global_load_dword v227, v[234:235], off
	global_load_dword v228, v[234:235], off offset:2048
	global_load_dword v229, v[236:237], off offset:-2048
	global_load_dword v230, v[236:237], off
	global_load_dword v231, v[236:237], off offset:2048
	s_waitcnt lgkmcnt(0)
	s_barrier
	v_xor_b32_e32 v102, 64, v137
	v_xor_b32_e32 v103, 64, v139
	ds_read_b128 v[36:39], v137
	ds_read_b128 v[76:79], v139
	ds_read_b128 v[98:101], v102
	ds_read_b128 v[174:177], v103
	ds_read_b128 v[40:43], v137 offset:8192
	ds_read_b128 v[80:83], v139 offset:8192
	ds_read_b128 v[178:181], v102 offset:8192
	ds_read_b128 v[182:185], v103 offset:8192
	ds_read_b128 v[44:47], v138
	ds_read_b128 v[84:87], v140
	ds_read_b128 v[186:189], v138 offset:4096
	ds_read_b128 v[232:235], v140 offset:4096
	ds_read_b128 v[236:239], v138 offset:8192
	ds_read_b128 v[240:243], v140 offset:8192
	ds_read_b128 v[244:247], v138 offset:12288
	s_waitcnt lgkmcnt(14)
	v_mfma_f32_16x16x32_bf16 v[36:39], v[0:3], v[36:39], 0
	ds_read_b128 v[248:251], v140 offset:12288

; #define LAS __attribute__((address_space(3)))
; __device__ __forceinline__ void rwkv_chunk_group(Frame& F, int bc, unsigned long long& tsub) {
;     ...
;         for (int q = 0; q < 2; ++q) { const int n0 = 16 * ((2 * w + q) & 3); aw[q] = Z4; aa[q] = Z4; ag[q] = Z4;
;             const LAS unsigned char* wp = L + L_LWA + (n0 + fr) * 128 + fq * 16; const LAS unsigned char* gp = L + L_LG + (n0 + fr) * 64 + fq * 16;
; #pragma unroll
;             for (int k = 0; k < 2; ++k) { aw[q] = __builtin_amdgcn_mfma_f32_16x16x32_bf16(xw[k], *(const LAS bf16x8*)(wp + k * 64), aw[q], 0, 0, 0); aa[q] = __builtin_amdgcn_mfma_f32_16x16x32_bf16(xa[k], *(const LAS bf16x8*)(wp + 8192 + k * 64), aa[q], 0, 0, 0); }
; #pragma unroll
;             for (int k = 0; k < 5; ++k) ag[q] = __builtin_amdgcn_mfma_f32_16x16x32_bf16(xg[k], *(const LAS bf16x8*)(gp + k * 4096), ag[q], 0, 0, 0);
	s_mov_b32 s68, s12
	s_waitcnt lgkmcnt(14)
	v_mfma_f32_16x16x32_bf16 v[76:79], v[0:3], v[76:79], 0
	ds_read_b128 v[88:91], v138 offset:16384
	v_readlane_b32 s12, v254, 2
	s_add_i32 s14, s68, s12
	s_waitcnt lgkmcnt(14)
	v_mfma_f32_16x16x32_bf16 v[36:39], v[4:7], v[98:101], v[36:39]
	ds_read_b128 v[98:101], v140 offset:16384
	s_lshl_b32 s14, s14, 6
	s_waitcnt lgkmcnt(14)
	v_mfma_f32_16x16x32_bf16 v[76:79], v[4:7], v[174:177], v[76:79]
	s_and_b32 s14, s14, 0x1c0
	s_waitcnt lgkmcnt(13)
	v_mfma_f32_16x16x32_bf16 v[40:43], v[8:11], v[40:43], 0
	s_add_i32 s66, s11, s14
	s_waitcnt lgkmcnt(12)
	v_mfma_f32_16x16x32_bf16 v[80:83], v[8:11], v[80:83], 0

; #define LAS __attribute__((address_space(3)))
; __device__ __forceinline__ void rwkv_chunk_group(Frame& F, int bc, unsigned long long& tsub) {
;     ...
;             for (int k = 0; k < 2; ++k) { aw[q] = __builtin_amdgcn_mfma_f32_16x16x32_bf16(xw[k], *(const LAS bf16x8*)(wp + k * 64), aw[q], 0, 0, 0); aa[q] = __builtin_amdgcn_mfma_f32_16x16x32_bf16(xa[k], *(const LAS bf16x8*)(wp + 8192 + k * 64), aa[q], 0, 0, 0); }
	s_waitcnt lgkmcnt(11)
	v_mfma_f32_16x16x32_bf16 v[40:43], v[12:15], v[178:181], v[40:43]

; #define LAS __attribute__((address_space(3)))
; __device__ __forceinline__ void rwkv_chunk_group(Frame& F, int bc, unsigned long long& tsub) {
;     ...
;             for (int k = 0; k < 2; ++k) { aw[q] = __builtin_amdgcn_mfma_f32_16x16x32_bf16(xw[k], *(const LAS bf16x8*)(wp + k * 64), aw[q], 0, 0, 0); aa[q] = __builtin_amdgcn_mfma_f32_16x16x32_bf16(xa[k], *(const LAS bf16x8*)(wp + 8192 + k * 64), aa[q], 0, 0, 0); }
; #pragma unroll
;             for (int k = 0; k < 5; ++k) ag[q] = __builtin_amdgcn_mfma_f32_16x16x32_bf16(xg[k], *(const LAS bf16x8*)(gp + k * 4096), ag[q], 0, 0, 0);
	s_waitcnt lgkmcnt(10)
	v_mfma_f32_16x16x32_bf16 v[80:83], v[12:15], v[182:185], v[80:83]
	s_mov_b32 s64, s12
	s_waitcnt lgkmcnt(9)
	v_mfma_f32_16x16x32_bf16 v[44:47], v[16:19], v[44:47], 0
	s_add_i32 s12, s68, 1
	s_waitcnt lgkmcnt(8)
	v_mfma_f32_16x16x32_bf16 v[84:87], v[16:19], v[84:87], 0
	s_add_i32 s13, s12, s64
	s_waitcnt lgkmcnt(7)
	v_mfma_f32_16x16x32_bf16 v[44:47], v[20:23], v[186:189], v[44:47]

; #define LAS __attribute__((address_space(3)))
; __device__ __forceinline__ void rwkv_chunk_group(Frame& F, int bc, unsigned long long& tsub) {
;     ...
;             for (int k = 0; k < 5; ++k) ag[q] = __builtin_amdgcn_mfma_f32_16x16x32_bf16(xg[k], *(const LAS bf16x8*)(gp + k * 4096), ag[q], 0, 0, 0);
	s_waitcnt lgkmcnt(6)
	v_mfma_f32_16x16x32_bf16 v[84:87], v[20:23], v[232:235], v[84:87]

; #define LAS __attribute__((address_space(3)))
; __device__ __forceinline__ void rwkv_chunk_group(Frame& F, int bc, unsigned long long& tsub) {
;     ...
;             for (int k = 0; k < 5; ++k) ag[q] = __builtin_amdgcn_mfma_f32_16x16x32_bf16(xg[k], *(const LAS bf16x8*)(gp + k * 4096), ag[q], 0, 0, 0);
	s_waitcnt lgkmcnt(5)
	v_mfma_f32_16x16x32_bf16 v[44:47], v[24:27], v[236:239], v[44:47]

; #define LAS __attribute__((address_space(3)))
; __device__ __forceinline__ void rwkv_chunk_group(Frame& F, int bc, unsigned long long& tsub) {
;     ...
;             for (int k = 0; k < 5; ++k) ag[q] = __builtin_amdgcn_mfma_f32_16x16x32_bf16(xg[k], *(const LAS bf16x8*)(gp + k * 4096), ag[q], 0, 0, 0);
	s_waitcnt lgkmcnt(4)
	v_mfma_f32_16x16x32_bf16 v[84:87], v[24:27], v[240:243], v[84:87]

; #define LAS __attribute__((address_space(3)))
; __device__ __forceinline__ void rwkv_chunk_group(Frame& F, int bc, unsigned long long& tsub) {
;     ...
;             for (int k = 0; k < 5; ++k) ag[q] = __builtin_amdgcn_mfma_f32_16x16x32_bf16(xg[k], *(const LAS bf16x8*)(gp + k * 4096), ag[q], 0, 0, 0);
	s_waitcnt lgkmcnt(3)
	v_mfma_f32_16x16x32_bf16 v[44:47], v[28:31], v[244:247], v[44:47]
	v_lshlrev_b32_e32 v197, 16, v162
	s_waitcnt lgkmcnt(2)
	v_mfma_f32_16x16x32_bf16 v[84:87], v[28:31], v[248:251], v[84:87]
	v_and_b32_e32 v199, 0xffff0000, v172
	s_waitcnt lgkmcnt(1)
	v_mfma_f32_16x16x32_bf16 v[44:47], v[32:35], v[88:91], v[44:47]
	s_ashr_i32 s67, s66, 31
	s_waitcnt lgkmcnt(0)
	v_mfma_f32_16x16x32_bf16 v[84:87], v[32:35], v[98:101], v[84:87]
	s_and_b32 s13, s13, 7
	s_nop 7
	s_nop 7


; #define LAS __attribute__((address_space(3)))
; __device__ __forceinline__ void rwkv_chunk_group(Frame& F, int bc, unsigned long long& tsub) {
;     ...
;                 *(LAS float*)(L + L_WL + (t * 65 + cc) * 4) = aw[q][v]; *(LAS float*)(L + L_AL + (t * 65 + cc) * 4) = aa[q][v]; *(LAS float*)(L + L_GL + (t * 65 + cc) * 4) = ag[q][v]; } }
	ds_write_b32 v111, v36

; #define LAS __attribute__((address_space(3)))
; __device__ __forceinline__ void rwkv_chunk_group(Frame& F, int bc, unsigned long long& tsub) {
;     ...
;                 *(LAS float*)(L + L_WL + (t * 65 + cc) * 4) = aw[q][v]; *(LAS float*)(L + L_AL + (t * 65 + cc) * 4) = aa[q][v]; *(LAS float*)(L + L_GL + (t * 65 + cc) * 4) = ag[q][v]; } }
	ds_write_b32 v111, v40 offset:16640

; #define LAS __attribute__((address_space(3)))
; __device__ __forceinline__ void rwkv_chunk_group(Frame& F, int bc, unsigned long long& tsub) {
;     ...
;                 *(LAS float*)(L + L_WL + (t * 65 + cc) * 4) = aw[q][v]; *(LAS float*)(L + L_AL + (t * 65 + cc) * 4) = aa[q][v]; *(LAS float*)(L + L_GL + (t * 65 + cc) * 4) = ag[q][v]; } }
	ds_write_b32 v111, v44 offset:33280

; #define LAS __attribute__((address_space(3)))
; __device__ __forceinline__ void rwkv_chunk_group(Frame& F, int bc, unsigned long long& tsub) {
;     ...
;                 *(LAS float*)(L + L_WL + (t * 65 + cc) * 4) = aw[q][v]; *(LAS float*)(L + L_AL + (t * 65 + cc) * 4) = aa[q][v]; *(LAS float*)(L + L_GL + (t * 65 + cc) * 4) = ag[q][v]; } }
	ds_write_b32 v112, v37

; #define LAS __attribute__((address_space(3)))
; __device__ __forceinline__ void rwkv_chunk_group(Frame& F, int bc, unsigned long long& tsub) {
;     ...
;                 *(LAS float*)(L + L_WL + (t * 65 + cc) * 4) = aw[q][v]; *(LAS float*)(L + L_AL + (t * 65 + cc) * 4) = aa[q][v]; *(LAS float*)(L + L_GL + (t * 65 + cc) * 4) = ag[q][v]; } }
	ds_write_b32 v112, v41 offset:16640

; #define LAS __attribute__((address_space(3)))
; __device__ __forceinline__ void rwkv_chunk_group(Frame& F, int bc, unsigned long long& tsub) {
;     ...
;                 *(LAS float*)(L + L_WL + (t * 65 + cc) * 4) = aw[q][v]; *(LAS float*)(L + L_AL + (t * 65 + cc) * 4) = aa[q][v]; *(LAS float*)(L + L_GL + (t * 65 + cc) * 4) = ag[q][v]; } }
	ds_write_b32 v112, v45 offset:33280

; #define LAS __attribute__((address_space(3)))
; __device__ __forceinline__ void rwkv_chunk_group(Frame& F, int bc, unsigned long long& tsub) {
;     ...
;                 *(LAS float*)(L + L_WL + (t * 65 + cc) * 4) = aw[q][v]; *(LAS float*)(L + L_AL + (t * 65 + cc) * 4) = aa[q][v]; *(LAS float*)(L + L_GL + (t * 65 + cc) * 4) = ag[q][v]; } }
	ds_write_b32 v113, v38

; #define LAS __attribute__((address_space(3)))
; __device__ __forceinline__ void rwkv_chunk_group(Frame& F, int bc, unsigned long long& tsub) {
;     ...
;                 *(LAS float*)(L + L_WL + (t * 65 + cc) * 4) = aw[q][v]; *(LAS float*)(L + L_AL + (t * 65 + cc) * 4) = aa[q][v]; *(LAS float*)(L + L_GL + (t * 65 + cc) * 4) = ag[q][v]; } }
	ds_write_b32 v113, v42 offset:16640

; #define LAS __attribute__((address_space(3)))
; __device__ __forceinline__ void rwkv_chunk_group(Frame& F, int bc, unsigned long long& tsub) {
;     ...
;                 *(LAS float*)(L + L_WL + (t * 65 + cc) * 4) = aw[q][v]; *(LAS float*)(L + L_AL + (t * 65 + cc) * 4) = aa[q][v]; *(LAS float*)(L + L_GL + (t * 65 + cc) * 4) = ag[q][v]; } }
	ds_write_b32 v113, v46 offset:33280

; #define LAS __attribute__((address_space(3)))
; __device__ __forceinline__ void rwkv_chunk_group(Frame& F, int bc, unsigned long long& tsub) {
;     ...
;                 *(LAS float*)(L + L_WL + (t * 65 + cc) * 4) = aw[q][v]; *(LAS float*)(L + L_AL + (t * 65 + cc) * 4) = aa[q][v]; *(LAS float*)(L + L_GL + (t * 65 + cc) * 4) = ag[q][v]; } }
	ds_write_b32 v114, v39

; #define LAS __attribute__((address_space(3)))
; __device__ __forceinline__ void rwkv_chunk_group(Frame& F, int bc, unsigned long long& tsub) {
;     ...
;                 *(LAS float*)(L + L_WL + (t * 65 + cc) * 4) = aw[q][v]; *(LAS float*)(L + L_AL + (t * 65 + cc) * 4) = aa[q][v]; *(LAS float*)(L + L_GL + (t * 65 + cc) * 4) = ag[q][v]; } }
	ds_write_b32 v114, v43 offset:16640

; #define LAS __attribute__((address_space(3)))
; __device__ __forceinline__ void rwkv_chunk_group(Frame& F, int bc, unsigned long long& tsub) {
;     ...
;                 *(LAS float*)(L + L_WL + (t * 65 + cc) * 4) = aw[q][v]; *(LAS float*)(L + L_AL + (t * 65 + cc) * 4) = aa[q][v]; *(LAS float*)(L + L_GL + (t * 65 + cc) * 4) = ag[q][v]; } }
	ds_write_b32 v114, v47 offset:33280

; #define LAS __attribute__((address_space(3)))
; __device__ __forceinline__ void rwkv_chunk_group(Frame& F, int bc, unsigned long long& tsub) {
;     ...
;                 *(LAS float*)(L + L_WL + (t * 65 + cc) * 4) = aw[q][v]; *(LAS float*)(L + L_AL + (t * 65 + cc) * 4) = aa[q][v]; *(LAS float*)(L + L_GL + (t * 65 + cc) * 4) = ag[q][v]; } }
	ds_write_b32 v115, v76

; #define LAS __attribute__((address_space(3)))
; __device__ __forceinline__ void rwkv_chunk_group(Frame& F, int bc, unsigned long long& tsub) {
;     ...
;                 *(LAS float*)(L + L_WL + (t * 65 + cc) * 4) = aw[q][v]; *(LAS float*)(L + L_AL + (t * 65 + cc) * 4) = aa[q][v]; *(LAS float*)(L + L_GL + (t * 65 + cc) * 4) = ag[q][v]; } }
	ds_write_b32 v115, v80 offset:16640

; #define LAS __attribute__((address_space(3)))
; __device__ __forceinline__ void rwkv_chunk_group(Frame& F, int bc, unsigned long long& tsub) {
;     ...
;                 *(LAS float*)(L + L_WL + (t * 65 + cc) * 4) = aw[q][v]; *(LAS float*)(L + L_AL + (t * 65 + cc) * 4) = aa[q][v]; *(LAS float*)(L + L_GL + (t * 65 + cc) * 4) = ag[q][v]; } }
	ds_write_b32 v115, v84 offset:33280

; #define LAS __attribute__((address_space(3)))
; __device__ __forceinline__ void rwkv_chunk_group(Frame& F, int bc, unsigned long long& tsub) {
;     ...
;                 *(LAS float*)(L + L_WL + (t * 65 + cc) * 4) = aw[q][v]; *(LAS float*)(L + L_AL + (t * 65 + cc) * 4) = aa[q][v]; *(LAS float*)(L + L_GL + (t * 65 + cc) * 4) = ag[q][v]; } }
	ds_write_b32 v116, v77

; #define LAS __attribute__((address_space(3)))
; __device__ __forceinline__ void rwkv_chunk_group(Frame& F, int bc, unsigned long long& tsub) {
;     ...
;                 *(LAS float*)(L + L_WL + (t * 65 + cc) * 4) = aw[q][v]; *(LAS float*)(L + L_AL + (t * 65 + cc) * 4) = aa[q][v]; *(LAS float*)(L + L_GL + (t * 65 + cc) * 4) = ag[q][v]; } }
	ds_write_b32 v116, v81 offset:16640

; #define LAS __attribute__((address_space(3)))
; __device__ __forceinline__ void rwkv_chunk_group(Frame& F, int bc, unsigned long long& tsub) {
;     ...
;                 *(LAS float*)(L + L_WL + (t * 65 + cc) * 4) = aw[q][v]; *(LAS float*)(L + L_AL + (t * 65 + cc) * 4) = aa[q][v]; *(LAS float*)(L + L_GL + (t * 65 + cc) * 4) = ag[q][v]; } }
	ds_write_b32 v116, v85 offset:33280

; #define LAS __attribute__((address_space(3)))
; __device__ __forceinline__ void rwkv_chunk_group(Frame& F, int bc, unsigned long long& tsub) {
;     ...
;                 *(LAS float*)(L + L_WL + (t * 65 + cc) * 4) = aw[q][v]; *(LAS float*)(L + L_AL + (t * 65 + cc) * 4) = aa[q][v]; *(LAS float*)(L + L_GL + (t * 65 + cc) * 4) = ag[q][v]; } }
	ds_write_b32 v117, v78

; #define LAS __attribute__((address_space(3)))
; __device__ __forceinline__ void rwkv_chunk_group(Frame& F, int bc, unsigned long long& tsub) {
;     ...
;                 *(LAS float*)(L + L_WL + (t * 65 + cc) * 4) = aw[q][v]; *(LAS float*)(L + L_AL + (t * 65 + cc) * 4) = aa[q][v]; *(LAS float*)(L + L_GL + (t * 65 + cc) * 4) = ag[q][v]; } }
	ds_write_b32 v117, v82 offset:16640

; #define LAS __attribute__((address_space(3)))
; __device__ __forceinline__ void rwkv_chunk_group(Frame& F, int bc, unsigned long long& tsub) {
;     ...
;                 *(LAS float*)(L + L_WL + (t * 65 + cc) * 4) = aw[q][v]; *(LAS float*)(L + L_AL + (t * 65 + cc) * 4) = aa[q][v]; *(LAS float*)(L + L_GL + (t * 65 + cc) * 4) = ag[q][v]; } }
	ds_write_b32 v117, v86 offset:33280

; #define LAS __attribute__((address_space(3)))
; __device__ __forceinline__ void rwkv_chunk_group(Frame& F, int bc, unsigned long long& tsub) {
;     ...
;                 *(LAS float*)(L + L_WL + (t * 65 + cc) * 4) = aw[q][v]; *(LAS float*)(L + L_AL + (t * 65 + cc) * 4) = aa[q][v]; *(LAS float*)(L + L_GL + (t * 65 + cc) * 4) = ag[q][v]; } }
	ds_write_b32 v118, v79

; #define LAS __attribute__((address_space(3)))
; __device__ __forceinline__ void rwkv_chunk_group(Frame& F, int bc, unsigned long long& tsub) {
;     ...
;                 *(LAS float*)(L + L_WL + (t * 65 + cc) * 4) = aw[q][v]; *(LAS float*)(L + L_AL + (t * 65 + cc) * 4) = aa[q][v]; *(LAS float*)(L + L_GL + (t * 65 + cc) * 4) = ag[q][v]; } }
	ds_write_b32 v118, v83 offset:16640

; #define LAS __attribute__((address_space(3)))
; __device__ __forceinline__ void rwkv_chunk_group(Frame& F, int bc, unsigned long long& tsub) {
;     ...
; #pragma unroll
;         for (int q = 0; q < 2; ++q) { const int tw = 2 * w + q, m0 = 16 * (tw >> 2), n0 = 16 * (tw & 3);
; #pragma unroll
;             for (int v = 0; v < 4; ++v) { const int t = m0 + 4 * fq + v, cc = n0 + fr;
;                 *(LAS float*)(L + L_WL + (t * 65 + cc) * 4) = aw[q][v]; *(LAS float*)(L + L_AL + (t * 65 + cc) * 4) = aa[q][v]; *(LAS float*)(L + L_GL + (t * 65 + cc) * 4) = ag[q][v]; } }
	ds_write_b32 v118, v87 offset:33280


; #define LBAR() asm volatile("s_waitcnt lgkmcnt(0)\n\ts_barrier" ::: "memory")
; __device__ __forceinline__ void rwkv_chunk_group(Frame& F, int bc, unsigned long long& tsub) {
;     ...
;         LBAR();
	s_waitcnt lgkmcnt(0)
	s_barrier


; __device__ __forceinline__ void rwkv_chunk_group(Frame& F, int bc, unsigned long long& tsub) {
;     ...
;         const int gc = h * 64 + ch;
;         const float mur = mu[gc], muk = mu[512 + gc], muv = mu[1024 + gc];
;         const float w0 = (PRM + 2048)[gc], a0 = (PRM + 2560)[gc], k_k = (PRM + 3072)[gc], k_a = (PRM + 3584)[gc], r_k = (PRM + 4096)[gc];
;         float rr[8], kp[8], vv[8], aa[8], bb[8], ld[8], vbv[8], ggv[8];
;         float pr = bf2f(raw[0][0]), pk = bf2f(raw[0][1]), pv = bf2f(raw[0][2]);
	s_waitcnt vmcnt(0)
	v_mov_b32_e32 v95, v224
	v_mov_b32_e32 v42, v225


; __device__ __forceinline__ void rwkv_chunk_group(Frame& F, int bc, unsigned long long& tsub) {
;     ...
;         float pr = bf2f(raw[0][0]), pk = bf2f(raw[0][1]), pv = bf2f(raw[0][2]);
	s_nop 0


; __device__ __forceinline__ void rwkv_chunk_group(Frame& F, int bc, unsigned long long& tsub) {
;     ...
;         const float mur = mu[gc], muk = mu[512 + gc], muv = mu[1024 + gc];
;         const float w0 = (PRM + 2048)[gc], a0 = (PRM + 2560)[gc], k_k = (PRM + 3072)[gc], k_a = (PRM + 3584)[gc], r_k = (PRM + 4096)[gc];
	v_mov_b32_e32 v52, v226


; __device__ __forceinline__ void rwkv_chunk_group(Frame& F, int bc, unsigned long long& tsub) {
;     ...
;         const float w0 = (PRM + 2048)[gc], a0 = (PRM + 2560)[gc], k_k = (PRM + 3072)[gc], k_a = (PRM + 3584)[gc], r_k = (PRM + 4096)[gc];
	v_mov_b32_e32 v45, v227


; __device__ __forceinline__ void rwkv_chunk_group(Frame& F, int bc, unsigned long long& tsub) {
;     ...
;         float pr = bf2f(raw[0][0]), pk = bf2f(raw[0][1]), pv = bf2f(raw[0][2]);
;         bf16* VBp = (bf16*)(F.ws + WS_VB) + (size_t)item * 4096; bf16* Gp = (bf16*)(F.ws + WS_G) + (size_t)item * 4096;
;         float run = 0.f; float kkv[8], icv[8], sq[8], bq[8];
; #pragma unroll
;         for (int tt = 0; tt < 8; ++tt) { const int t = tb + tt;
;             const float cr = bf2f(raw[tt + 1][0]), ck = bf2f(raw[tt + 1][1]), cv = bf2f(raw[tt + 1][2]);
	v_lshlrev_b32_e32 v82, 16, v155
	v_and_b32_e32 v77, 0xffff0000, v167

; __device__ __forceinline__ void rwkv_chunk_group(Frame& F, int bc, unsigned long long& tsub) {
;     ...
;         const float w0 = (PRM + 2048)[gc], a0 = (PRM + 2560)[gc], k_k = (PRM + 3072)[gc], k_a = (PRM + 3584)[gc], r_k = (PRM + 4096)[gc];
	v_mov_b32_e32 v43, v228


; __device__ __forceinline__ void rwkv_chunk_group(Frame& F, int bc, unsigned long long& tsub) {
;     ...
;             const float cr = bf2f(raw[tt + 1][0]), ck = bf2f(raw[tt + 1][1]), cv = bf2f(raw[tt + 1][2]);
	v_lshlrev_b32_e32 v76, 16, v167
	v_and_b32_e32 v79, 0xffff0000, v166


; __device__ __forceinline__ void rwkv_chunk_group(Frame& F, int bc, unsigned long long& tsub) {
;     ...
;         const float w0 = (PRM + 2048)[gc], a0 = (PRM + 2560)[gc], k_k = (PRM + 3072)[gc], k_a = (PRM + 3584)[gc], r_k = (PRM + 4096)[gc];
;         float rr[8], kp[8], vv[8], aa[8], bb[8], ld[8], vbv[8], ggv[8];
;         float pr = bf2f(raw[0][0]), pk = bf2f(raw[0][1]), pv = bf2f(raw[0][2]);
;         bf16* VBp = (bf16*)(F.ws + WS_VB) + (size_t)item * 4096; bf16* Gp = (bf16*)(F.ws + WS_G) + (size_t)item * 4096;
;         float run = 0.f; float kkv[8], icv[8], sq[8], bq[8];
; #pragma unroll
;         for (int tt = 0; tt < 8; ++tt) { const int t = tb + tt;
;             const float cr = bf2f(raw[tt + 1][0]), ck = bf2f(raw[tt + 1][1]), cv = bf2f(raw[tt + 1][2]);
	v_mov_b32_e32 v44, v229
	v_lshlrev_b32_e32 v78, 16, v166

; __device__ __forceinline__ void rwkv_chunk_group(Frame& F, int bc, unsigned long long& tsub) {
;     ...
;         const float w0 = (PRM + 2048)[gc], a0 = (PRM + 2560)[gc], k_k = (PRM + 3072)[gc], k_a = (PRM + 3584)[gc], r_k = (PRM + 4096)[gc];
	v_mov_b32_e32 v46, v230


; __device__ __forceinline__ void rwkv_chunk_group(Frame& F, int bc, unsigned long long& tsub) {
;     ...
;             const float cr = bf2f(raw[tt + 1][0]), ck = bf2f(raw[tt + 1][1]), cv = bf2f(raw[tt + 1][2]);
	v_lshlrev_b32_e32 v86, 16, v157
	v_and_b32_e32 v91, 0xffff0000, v168

; __device__ __forceinline__ void rwkv_chunk_group(Frame& F, int bc, unsigned long long& tsub) {
;     ...
;         float pr = bf2f(raw[0][0]), pk = bf2f(raw[0][1]), pv = bf2f(raw[0][2]);
;         bf16* VBp = (bf16*)(F.ws + WS_VB) + (size_t)item * 4096; bf16* Gp = (bf16*)(F.ws + WS_G) + (size_t)item * 4096;
;         float run = 0.f; float kkv[8], icv[8], sq[8], bq[8];
; #pragma unroll
;         for (int tt = 0; tt < 8; ++tt) { const int t = tb + tt;
;             const float cr = bf2f(raw[tt + 1][0]), ck = bf2f(raw[tt + 1][1]), cv = bf2f(raw[tt + 1][2]);
;             const float r = cr + (pr - cr) * mur, k = ck + (pk - ck) * muk, v = cv + (pv - cv) * muv; pr = cr; pk = ck; pv = cv;
	v_mov_b32_e32 v103, v231
	v_lshlrev_b32_e32 v36, 16, v153
	v_lshlrev_b32_e32 v37, 16, v154
	v_sub_f32_e32 v36, v36, v37


; #define LAS __attribute__((address_space(3)))
; __device__ __forceinline__ void rwkv_chunk_group(Frame& F, int bc, unsigned long long& tsub) {
;     ...
;         for (int tt = 0; tt < 8; ++tt) { const int t = tb + tt;
;             const float cr = bf2f(raw[tt + 1][0]), ck = bf2f(raw[tt + 1][1]), cv = bf2f(raw[tt + 1][2]);
;             const float r = cr + (pr - cr) * mur, k = ck + (pk - ck) * muk, v = cv + (pv - cv) * muv; pr = cr; pk = ck; pv = cv;
;             const float wl = *(const LAS float*)(L + L_WL + (t * 65 + ch) * 4), al = *(const LAS float*)(L + L_AL + (t * 65 + ch) * 4), gl = *(const LAS float*)(L + L_GL + (t * 65 + ch) * 4);
	ds_read_b32 v38, v119 offset:16640
	ds_read_b32 v47, v119 offset:33280
	ds_read_b32 v177, v120 offset:33280
	ds_read_b32 v185, v122 offset:33280
	ds_read_b32 v191, v125 offset:16640
	v_lshlrev_b32_e32 v90, 16, v168
	v_and_b32_e32 v85, 0xffff0000, v169
	ds_read_b32 v182, v121 offset:33280
	ds_read_b32 v96, v124 offset:16640
	ds_read_b32 v189, v123 offset:33280
	ds_read_b32 v193, v124 offset:33280
	ds_read_b32 v194, v125 offset:33280
	s_waitcnt vmcnt(7)
	v_fma_f32 v173, v36, v95, v37

; __device__ __forceinline__ void rwkv_chunk_group(Frame& F, int bc, unsigned long long& tsub) {
;     ...
;             const float z = -(w0 + wl); const float sp = fmaxf(z, 0.f) + __logf(1.f + __expf(-fabsf(z)));
	ds_read_b32 v36, v119
	s_waitcnt vmcnt(4) lgkmcnt(0)
	v_add_f32_e32 v36, v45, v36
	v_max_f32_e64 v39, -v36, 0
	v_mul_f32_e64 v36, |v36|, s1
	v_exp_f32_e32 v36, v36
	s_nop 0
	v_add_f32_e32 v36, 1.0, v36

; __device__ __forceinline__ void rwkv_chunk_group(Frame& F, int bc, unsigned long long& tsub) {
;     ...
;             const float z = -(w0 + wl); const float sp = fmaxf(z, 0.f) + __logf(1.f + __expf(-fabsf(z)));
	s_nop 1


; __device__ __forceinline__ void rwkv_chunk_group(Frame& F, int bc, unsigned long long& tsub) {
;     ...
;             const float z = -(w0 + wl); const float sp = fmaxf(z, 0.f) + __logf(1.f + __expf(-fabsf(z)));
	v_log_f32_e32 v36, v36
	s_nop 0
	v_mul_f32_e32 v40, 0x3f317217, v36
	v_fma_f32 v40, v36, s9, -v40
	v_fmac_f32_e32 v40, 0x3377d1cf, v36
	v_fmac_f32_e32 v40, 0x3f317217, v36

; __device__ __forceinline__ void rwkv_chunk_group(Frame& F, int bc, unsigned long long& tsub) {
;     ...
;             const float z = -(w0 + wl); const float sp = fmaxf(z, 0.f) + __logf(1.f + __expf(-fabsf(z)));
	s_nop 1
	v_mov_b32_e32 v36, v40


; __device__ __forceinline__ void rwkv_chunk_group(Frame& F, int bc, unsigned long long& tsub) {
;     ...
;             const float z = -(w0 + wl); const float sp = fmaxf(z, 0.f) + __logf(1.f + __expf(-fabsf(z)));
	v_add_f32_e32 v36, v39, v36

; __device__ __forceinline__ float sigmoidf_(float x) { return __builtin_amdgcn_rcpf(1.0f + __expf(-x)); }
; __device__ __forceinline__ void rwkv_chunk_group(Frame& F, int bc, unsigned long long& tsub) {
;     ...
;             const float lgd = -__expf(-sp - 0.5f);
;             const float ic = sigmoidf_(a0 + al);
	ds_read_b32 v39, v120
	v_sub_f32_e32 v36, -0.5, v36
	v_mul_f32_e32 v36, 0x3fb8aa3b, v36
	v_exp_f32_e32 v102, v36
	s_waitcnt vmcnt(3)
	v_add_f32_e32 v36, v43, v38
	v_mul_f32_e32 v36, 0xbfb8aa3b, v36

; #define LAS __attribute__((address_space(3)))
; __device__ __forceinline__ float sigmoidf_(float x) { return __builtin_amdgcn_rcpf(1.0f + __expf(-x)); }
; __device__ __forceinline__ void rwkv_chunk_group(Frame& F, int bc, unsigned long long& tsub) {
;     ...
;         for (int tt = 0; tt < 8; ++tt) { const int t = tb + tt;
;             const float cr = bf2f(raw[tt + 1][0]), ck = bf2f(raw[tt + 1][1]), cv = bf2f(raw[tt + 1][2]);
;             const float r = cr + (pr - cr) * mur, k = ck + (pk - ck) * muk, v = cv + (pv - cv) * muv; pr = cr; pk = ck; pv = cv;
;             const float wl = *(const LAS float*)(L + L_WL + (t * 65 + ch) * 4), al = *(const LAS float*)(L + L_AL + (t * 65 + ch) * 4), gl = *(const LAS float*)(L + L_GL + (t * 65 + ch) * 4);
;             const float z = -(w0 + wl); const float sp = fmaxf(z, 0.f) + __logf(1.f + __expf(-fabsf(z)));
;             const float lgd = -__expf(-sp - 0.5f);
;             const float ic = sigmoidf_(a0 + al);
;             const float kv = k * k_k; const float kq = k * (1.f + (ic - 1.f) * k_a);
	v_exp_f32_e32 v36, v36
	ds_read_b32 v40, v120 offset:16640
	s_waitcnt lgkmcnt(1)
	v_add_f32_e32 v39, v45, v39
	v_max_f32_e64 v41, -v39, 0
	v_mul_f32_e64 v39, |v39|, s1
	v_exp_f32_e32 v39, v39
	v_add_f32_e32 v36, 1.0, v36
	v_rcp_f32_e32 v38, v36
	v_sub_f32_e32 v36, v37, v82
	v_fma_f32 v174, v36, v95, v82
	v_and_b32_e32 v37, 0xffff0000, v161
	v_lshlrev_b32_e32 v36, 16, v161
	v_add_f32_e32 v39, 1.0, v39
	v_pk_add_f32 v[36:37], v[36:37], v[76:77] neg_lo:[0,1] neg_hi:[0,1]

; __device__ __forceinline__ void rwkv_chunk_group(Frame& F, int bc, unsigned long long& tsub) {
;     ...
;             const float r = cr + (pr - cr) * mur, k = ck + (pk - ck) * muk, v = cv + (pv - cv) * muv; pr = cr; pk = ck; pv = cv;
	v_pk_fma_f32 v[36:37], v[36:37], v[52:53], v[76:77] op_sel_hi:[1,0,1]
	s_nop 0


; __device__ __forceinline__ void rwkv_chunk_group(Frame& F, int bc, unsigned long long& tsub) {
;     ...
;             const float z = -(w0 + wl); const float sp = fmaxf(z, 0.f) + __logf(1.f + __expf(-fabsf(z)));
	v_log_f32_e32 v39, v39
	s_nop 0
	v_mul_f32_e32 v76, 0x3f317217, v39
	v_fma_f32 v76, v39, s9, -v76
	v_fmac_f32_e32 v76, 0x3377d1cf, v39
	v_fmac_f32_e32 v76, 0x3f317217, v39

; __device__ __forceinline__ void rwkv_chunk_group(Frame& F, int bc, unsigned long long& tsub) {
;     ...
;             const float z = -(w0 + wl); const float sp = fmaxf(z, 0.f) + __logf(1.f + __expf(-fabsf(z)));
	s_nop 1
	v_mov_b32_e32 v39, v76


; __device__ __forceinline__ float sigmoidf_(float x) { return __builtin_amdgcn_rcpf(1.0f + __expf(-x)); }
; __device__ __forceinline__ void rwkv_chunk_group(Frame& F, int bc, unsigned long long& tsub) {
;     ...
;             const float z = -(w0 + wl); const float sp = fmaxf(z, 0.f) + __logf(1.f + __expf(-fabsf(z)));
;             const float lgd = -__expf(-sp - 0.5f);
;             const float ic = sigmoidf_(a0 + al);
;             const float kv = k * k_k; const float kq = k * (1.f + (ic - 1.f) * k_a);
;             kkv[tt] = kv; icv[tt] = ic; sq[tt] = kv * kv; bq[tt] = r * kq * r_k;
;             rr[tt] = r; kp[tt] = kq; vv[tt] = v; run += lgd; ld[tt] = run; ggv[tt] = gl;
	v_add_f32_e32 v39, v41, v39
	v_sub_f32_e32 v39, -0.5, v39
	v_mul_f32_e32 v39, 0x3fb8aa3b, v39
	v_exp_f32_e32 v76, v39
	s_waitcnt lgkmcnt(0)
	v_add_f32_e32 v39, v43, v40
	v_mul_f32_e32 v39, 0xbfb8aa3b, v39
	v_exp_f32_e32 v39, v39
	v_and_b32_e32 v41, 0xffff0000, v160
	v_lshlrev_b32_e32 v40, 16, v160
	v_pk_add_f32 v[40:41], v[40:41], v[78:79] neg_lo:[0,1] neg_hi:[0,1]
	v_add_f32_e32 v39, 1.0, v39
	v_rcp_f32_e32 v39, v39
	v_pk_fma_f32 v[80:81], v[40:41], v[42:43], v[78:79] op_sel_hi:[1,0,1]
	v_sub_f32_e64 v176, -v102, v76
	v_lshlrev_b32_e32 v76, 16, v156
	v_pk_add_f32 v[40:41], v[38:39], -1.0 op_sel_hi:[1,0]
	s_waitcnt vmcnt(1)
	v_pk_fma_f32 v[40:41], v[46:47], v[40:41], 1.0 op_sel_hi:[0,1,0]
	v_pk_mul_f32 v[40:41], v[80:81], v[40:41]
	s_nop 0
	v_mul_f32_e32 v78, v173, v40
	s_waitcnt vmcnt(0)
	v_mul_f32_e32 v101, v103, v78
	v_mul_f32_e32 v78, v174, v41
	v_mul_f32_e32 v100, v103, v78
	v_sub_f32_e32 v78, v82, v76
	v_fma_f32 v175, v78, v95, v76

; #define LAS __attribute__((address_space(3)))
; __device__ __forceinline__ void rwkv_chunk_group(Frame& F, int bc, unsigned long long& tsub) {
;     ...
;             const float wl = *(const LAS float*)(L + L_WL + (t * 65 + ch) * 4), al = *(const LAS float*)(L + L_AL + (t * 65 + ch) * 4), gl = *(const LAS float*)(L + L_GL + (t * 65 + ch) * 4);
	ds_read_b32 v78, v121

; #define LAS __attribute__((address_space(3)))
; __device__ __forceinline__ float sigmoidf_(float x) { return __builtin_amdgcn_rcpf(1.0f + __expf(-x)); }
; __device__ __forceinline__ void rwkv_chunk_group(Frame& F, int bc, unsigned long long& tsub) {
;     ...
;             const float r = cr + (pr - cr) * mur, k = ck + (pk - ck) * muk, v = cv + (pv - cv) * muv; pr = cr; pk = ck; pv = cv;
;             const float wl = *(const LAS float*)(L + L_WL + (t * 65 + ch) * 4), al = *(const LAS float*)(L + L_AL + (t * 65 + ch) * 4), gl = *(const LAS float*)(L + L_GL + (t * 65 + ch) * 4);
;             const float z = -(w0 + wl); const float sp = fmaxf(z, 0.f) + __logf(1.f + __expf(-fabsf(z)));
;             const float lgd = -__expf(-sp - 0.5f);
;             const float ic = sigmoidf_(a0 + al);
	ds_read_b32 v82, v121 offset:16640
	v_sub_f32_e32 v76, v76, v86
	v_fma_f32 v178, v76, v95, v86
	s_waitcnt lgkmcnt(1)
	v_add_f32_e32 v78, v45, v78
	v_max_f32_e64 v83, -v78, 0
	v_mul_f32_e64 v78, |v78|, s1
	v_exp_f32_e32 v78, v78
	s_waitcnt lgkmcnt(0)
	v_add_f32_e32 v82, v43, v82
	v_mul_f32_e32 v82, 0xbfb8aa3b, v82
	v_exp_f32_e32 v82, v82
	v_add_f32_e32 v78, 1.0, v78

; __device__ __forceinline__ float sigmoidf_(float x) { return __builtin_amdgcn_rcpf(1.0f + __expf(-x)); }
; __device__ __forceinline__ void rwkv_chunk_group(Frame& F, int bc, unsigned long long& tsub) {
;     ...
;             const float z = -(w0 + wl); const float sp = fmaxf(z, 0.f) + __logf(1.f + __expf(-fabsf(z)));
;             const float lgd = -__expf(-sp - 0.5f);
;             const float ic = sigmoidf_(a0 + al);
	v_add_f32_e32 v82, 1.0, v82
	s_nop 0


; __device__ __forceinline__ float sigmoidf_(float x) { return __builtin_amdgcn_rcpf(1.0f + __expf(-x)); }
; __device__ __forceinline__ void rwkv_chunk_group(Frame& F, int bc, unsigned long long& tsub) {
;     ...
;             const float z = -(w0 + wl); const float sp = fmaxf(z, 0.f) + __logf(1.f + __expf(-fabsf(z)));
;             const float lgd = -__expf(-sp - 0.5f);
;             const float ic = sigmoidf_(a0 + al);
	v_log_f32_e32 v78, v78
	v_rcp_f32_e32 v82, v82
	v_mul_f32_e32 v84, 0x3f317217, v78
	v_fma_f32 v84, v78, s9, -v84
	v_fmac_f32_e32 v84, 0x3377d1cf, v78
	v_fmac_f32_e32 v84, 0x3f317217, v78

; __device__ __forceinline__ void rwkv_chunk_group(Frame& F, int bc, unsigned long long& tsub) {
;     ...
;             const float z = -(w0 + wl); const float sp = fmaxf(z, 0.f) + __logf(1.f + __expf(-fabsf(z)));
	s_nop 1
	v_mov_b32_e32 v78, v84


; __device__ __forceinline__ void rwkv_chunk_group(Frame& F, int bc, unsigned long long& tsub) {
;     ...
;             const float z = -(w0 + wl); const float sp = fmaxf(z, 0.f) + __logf(1.f + __expf(-fabsf(z)));
;             const float lgd = -__expf(-sp - 0.5f);
	v_add_f32_e32 v78, v83, v78
	v_sub_f32_e32 v78, -0.5, v78
	v_mul_f32_e32 v78, 0x3fb8aa3b, v78
	v_exp_f32_e32 v78, v78

; #define LAS __attribute__((address_space(3)))
; __device__ __forceinline__ float sigmoidf_(float x) { return __builtin_amdgcn_rcpf(1.0f + __expf(-x)); }
; __device__ __forceinline__ void rwkv_chunk_group(Frame& F, int bc, unsigned long long& tsub) {
;     ...
;             const float wl = *(const LAS float*)(L + L_WL + (t * 65 + ch) * 4), al = *(const LAS float*)(L + L_AL + (t * 65 + ch) * 4), gl = *(const LAS float*)(L + L_GL + (t * 65 + ch) * 4);
;             const float z = -(w0 + wl); const float sp = fmaxf(z, 0.f) + __logf(1.f + __expf(-fabsf(z)));
;             const float lgd = -__expf(-sp - 0.5f);
;             const float ic = sigmoidf_(a0 + al);
;             const float kv = k * k_k; const float kq = k * (1.f + (ic - 1.f) * k_a);
;             kkv[tt] = kv; icv[tt] = ic; sq[tt] = kv * kv; bq[tt] = r * kq * r_k;
;             rr[tt] = r; kp[tt] = kq; vv[tt] = v; run += lgd; ld[tt] = run; ggv[tt] = gl;
	ds_read_b32 v83, v122 offset:16640
	v_lshlrev_b32_e32 v84, 16, v169
	v_sub_f32_e32 v179, v176, v78

; #define LAS __attribute__((address_space(3)))
; __device__ __forceinline__ void rwkv_chunk_group(Frame& F, int bc, unsigned long long& tsub) {
;     ...
;             const float r = cr + (pr - cr) * mur, k = ck + (pk - ck) * muk, v = cv + (pv - cv) * muv; pr = cr; pk = ck; pv = cv;
;             const float wl = *(const LAS float*)(L + L_WL + (t * 65 + ch) * 4), al = *(const LAS float*)(L + L_AL + (t * 65 + ch) * 4), gl = *(const LAS float*)(L + L_GL + (t * 65 + ch) * 4);
;             const float z = -(w0 + wl); const float sp = fmaxf(z, 0.f) + __logf(1.f + __expf(-fabsf(z)));
	ds_read_b32 v78, v122
	v_pk_mov_b32 v[76:77], v[76:77], v[84:85] op_sel:[1,0]
	s_waitcnt lgkmcnt(0)
	v_add_f32_e32 v78, v45, v78
	v_max_f32_e64 v87, -v78, 0
	v_mul_f32_e64 v78, |v78|, s1
	v_exp_f32_e32 v78, v78
	v_pk_add_f32 v[76:77], v[76:77], v[84:85] neg_lo:[0,1] neg_hi:[0,1]
	v_add_f32_e32 v78, 1.0, v78

; __device__ __forceinline__ void rwkv_chunk_group(Frame& F, int bc, unsigned long long& tsub) {
;     ...
;             const float r = cr + (pr - cr) * mur, k = ck + (pk - ck) * muk, v = cv + (pv - cv) * muv; pr = cr; pk = ck; pv = cv;
	v_pk_fma_f32 v[76:77], v[76:77], v[52:53], v[84:85] op_sel_hi:[1,0,1]
	s_nop 0


; __device__ __forceinline__ void rwkv_chunk_group(Frame& F, int bc, unsigned long long& tsub) {
;     ...
;             const float z = -(w0 + wl); const float sp = fmaxf(z, 0.f) + __logf(1.f + __expf(-fabsf(z)));
	v_log_f32_e32 v78, v78
	s_nop 0
	v_mul_f32_e32 v88, 0x3f317217, v78
	v_fma_f32 v88, v78, s9, -v88
	v_fmac_f32_e32 v88, 0x3377d1cf, v78
	v_fmac_f32_e32 v88, 0x3f317217, v78

; __device__ __forceinline__ void rwkv_chunk_group(Frame& F, int bc, unsigned long long& tsub) {
;     ...
;             const float z = -(w0 + wl); const float sp = fmaxf(z, 0.f) + __logf(1.f + __expf(-fabsf(z)));
	s_nop 1
	v_mov_b32_e32 v78, v88


; __device__ __forceinline__ float sigmoidf_(float x) { return __builtin_amdgcn_rcpf(1.0f + __expf(-x)); }
; __device__ __forceinline__ void rwkv_chunk_group(Frame& F, int bc, unsigned long long& tsub) {
;     ...
;             const float z = -(w0 + wl); const float sp = fmaxf(z, 0.f) + __logf(1.f + __expf(-fabsf(z)));
;             const float lgd = -__expf(-sp - 0.5f);
;             const float ic = sigmoidf_(a0 + al);
;             const float kv = k * k_k; const float kq = k * (1.f + (ic - 1.f) * k_a);
;             kkv[tt] = kv; icv[tt] = ic; sq[tt] = kv * kv; bq[tt] = r * kq * r_k;
;             rr[tt] = r; kp[tt] = kq; vv[tt] = v; run += lgd; ld[tt] = run; ggv[tt] = gl;
	v_add_f32_e32 v78, v87, v78
	v_sub_f32_e32 v78, -0.5, v78
	v_mul_f32_e32 v78, 0x3fb8aa3b, v78
	v_exp_f32_e32 v87, v78
	v_add_f32_e32 v78, v43, v83
	v_mul_f32_e32 v78, 0xbfb8aa3b, v78
	v_exp_f32_e32 v78, v78
	v_sub_f32_e32 v181, v179, v87
	v_lshlrev_b32_e32 v87, 16, v158
	v_sub_f32_e32 v86, v86, v87
	v_add_f32_e32 v78, 1.0, v78
	v_rcp_f32_e32 v83, v78
	v_pk_mov_b32 v[78:79], v[78:79], v[90:91] op_sel:[1,0]
	v_fma_f32 v180, v86, v95, v87
	v_pk_add_f32 v[78:79], v[78:79], v[90:91] neg_lo:[0,1] neg_hi:[0,1]

; __device__ __forceinline__ void rwkv_chunk_group(Frame& F, int bc, unsigned long long& tsub) {
;     ...
;             const float kv = k * k_k; const float kq = k * (1.f + (ic - 1.f) * k_a);
;             kkv[tt] = kv; icv[tt] = ic; sq[tt] = kv * kv; bq[tt] = r * kq * r_k;
	v_pk_fma_f32 v[88:89], v[78:79], v[42:43], v[90:91] op_sel_hi:[1,0,1]
	v_pk_add_f32 v[78:79], v[82:83], -1.0 op_sel_hi:[1,0]
	ds_read_b32 v86, v123
	v_pk_fma_f32 v[78:79], v[46:47], v[78:79], 1.0 op_sel_hi:[0,1,0]
	v_pk_mul_f32 v[78:79], v[88:89], v[78:79]
	s_nop 0
	v_mul_f32_e32 v92, v175, v78
	v_mul_f32_e32 v187, v103, v92
	v_mul_f32_e32 v92, v178, v79
	v_mul_f32_e32 v186, v103, v92

; __device__ __forceinline__ void rwkv_chunk_group(Frame& F, int bc, unsigned long long& tsub) {
;     ...
;             const float z = -(w0 + wl); const float sp = fmaxf(z, 0.f) + __logf(1.f + __expf(-fabsf(z)));
	ds_read_b32 v92, v123 offset:16640
	s_waitcnt lgkmcnt(1)
	v_add_f32_e32 v86, v45, v86
	v_max_f32_e64 v93, -v86, 0
	v_mul_f32_e64 v86, |v86|, s1
	v_exp_f32_e32 v86, v86
	s_nop 0
	v_add_f32_e32 v86, 1.0, v86

; __device__ __forceinline__ void rwkv_chunk_group(Frame& F, int bc, unsigned long long& tsub) {
;     ...
;             const float z = -(w0 + wl); const float sp = fmaxf(z, 0.f) + __logf(1.f + __expf(-fabsf(z)));
	s_nop 1


; __device__ __forceinline__ void rwkv_chunk_group(Frame& F, int bc, unsigned long long& tsub) {
;     ...
;             const float z = -(w0 + wl); const float sp = fmaxf(z, 0.f) + __logf(1.f + __expf(-fabsf(z)));
	v_log_f32_e32 v86, v86
	s_nop 0
	v_mul_f32_e32 v94, 0x3f317217, v86
	v_fma_f32 v94, v86, s9, -v94
	v_fmac_f32_e32 v94, 0x3377d1cf, v86
	v_fmac_f32_e32 v94, 0x3f317217, v86

; __device__ __forceinline__ void rwkv_chunk_group(Frame& F, int bc, unsigned long long& tsub) {
;     ...
;             const float z = -(w0 + wl); const float sp = fmaxf(z, 0.f) + __logf(1.f + __expf(-fabsf(z)));
	s_nop 1
	v_mov_b32_e32 v86, v94


; __device__ __forceinline__ void rwkv_chunk_group(Frame& F, int bc, unsigned long long& tsub) {
;     ...
;             const float r = cr + (pr - cr) * mur, k = ck + (pk - ck) * muk, v = cv + (pv - cv) * muv; pr = cr; pk = ck; pv = cv;
	v_lshlrev_b32_e32 v94, 16, v159
	v_sub_f32_e32 v87, v87, v94
	v_fma_f32 v183, v87, v95, v94

; __device__ __forceinline__ float sigmoidf_(float x) { return __builtin_amdgcn_rcpf(1.0f + __expf(-x)); }
; __device__ __forceinline__ void rwkv_chunk_group(Frame& F, int bc, unsigned long long& tsub) {
;     ...
;             const float z = -(w0 + wl); const float sp = fmaxf(z, 0.f) + __logf(1.f + __expf(-fabsf(z)));
;             const float lgd = -__expf(-sp - 0.5f);
;             const float ic = sigmoidf_(a0 + al);
	ds_read_b32 v87, v124
	v_add_f32_e32 v86, v93, v86
	v_sub_f32_e32 v86, -0.5, v86
	v_mul_f32_e32 v86, 0x3fb8aa3b, v86
	v_exp_f32_e32 v93, v86
	s_waitcnt lgkmcnt(0)
	v_add_f32_e32 v87, v45, v87
	v_max_f32_e64 v97, -v87, 0
	v_mul_f32_e64 v87, |v87|, s1
	v_exp_f32_e32 v87, v87
	v_add_f32_e32 v86, v43, v92
	v_mul_f32_e32 v86, 0xbfb8aa3b, v86
	v_exp_f32_e32 v86, v86
	v_add_f32_e32 v87, 1.0, v87

; __device__ __forceinline__ void rwkv_chunk_group(Frame& F, int bc, unsigned long long& tsub) {
;     ...
;             rr[tt] = r; kp[tt] = kq; vv[tt] = v; run += lgd; ld[tt] = run; ggv[tt] = gl;
	v_sub_f32_e32 v184, v181, v93
	v_add_f32_e32 v86, 1.0, v86


; #define LAS __attribute__((address_space(3)))
; __device__ __forceinline__ float sigmoidf_(float x) { return __builtin_amdgcn_rcpf(1.0f + __expf(-x)); }
; __device__ __forceinline__ void rwkv_chunk_group(Frame& F, int bc, unsigned long long& tsub) {
;     ...
;             const float r = cr + (pr - cr) * mur, k = ck + (pk - ck) * muk, v = cv + (pv - cv) * muv; pr = cr; pk = ck; pv = cv;
;             const float wl = *(const LAS float*)(L + L_WL + (t * 65 + ch) * 4), al = *(const LAS float*)(L + L_AL + (t * 65 + ch) * 4), gl = *(const LAS float*)(L + L_GL + (t * 65 + ch) * 4);
;             const float z = -(w0 + wl); const float sp = fmaxf(z, 0.f) + __logf(1.f + __expf(-fabsf(z)));
;             const float lgd = -__expf(-sp - 0.5f);
;             const float ic = sigmoidf_(a0 + al);
	v_log_f32_e32 v87, v87
	v_rcp_f32_e32 v86, v86
	v_sub_f32_e32 v94, v94, v197
	v_and_b32_e32 v93, 0xffff0000, v171
	v_mul_f32_e32 v98, 0x3f317217, v87
	v_fma_f32 v98, v87, s9, -v98
	v_fmac_f32_e32 v98, 0x3377d1cf, v87
	v_fmac_f32_e32 v98, 0x3f317217, v87

; #define LAS __attribute__((address_space(3)))
; __device__ __forceinline__ void rwkv_chunk_group(Frame& F, int bc, unsigned long long& tsub) {
;     ...
;             const float cr = bf2f(raw[tt + 1][0]), ck = bf2f(raw[tt + 1][1]), cv = bf2f(raw[tt + 1][2]);
;             const float r = cr + (pr - cr) * mur, k = ck + (pk - ck) * muk, v = cv + (pv - cv) * muv; pr = cr; pk = ck; pv = cv;
;             const float wl = *(const LAS float*)(L + L_WL + (t * 65 + ch) * 4), al = *(const LAS float*)(L + L_AL + (t * 65 + ch) * 4), gl = *(const LAS float*)(L + L_GL + (t * 65 + ch) * 4);
;             const float z = -(w0 + wl); const float sp = fmaxf(z, 0.f) + __logf(1.f + __expf(-fabsf(z)));
	v_lshlrev_b32_e32 v92, 16, v171
	v_pk_mov_b32 v[84:85], v[84:85], v[92:93] op_sel:[1,0]
	v_mov_b32_e32 v87, v98


; __device__ __forceinline__ float sigmoidf_(float x) { return __builtin_amdgcn_rcpf(1.0f + __expf(-x)); }
; __device__ __forceinline__ void rwkv_chunk_group(Frame& F, int bc, unsigned long long& tsub) {
;     ...
;             const float z = -(w0 + wl); const float sp = fmaxf(z, 0.f) + __logf(1.f + __expf(-fabsf(z)));
;             const float lgd = -__expf(-sp - 0.5f);
;             const float ic = sigmoidf_(a0 + al);
;             const float kv = k * k_k; const float kq = k * (1.f + (ic - 1.f) * k_a);
;             kkv[tt] = kv; icv[tt] = ic; sq[tt] = kv * kv; bq[tt] = r * kq * r_k;
;             rr[tt] = r; kp[tt] = kq; vv[tt] = v; run += lgd; ld[tt] = run; ggv[tt] = gl;
	v_add_f32_e32 v87, v97, v87
	v_sub_f32_e32 v87, -0.5, v87
	v_mul_f32_e32 v87, 0x3fb8aa3b, v87
	v_exp_f32_e32 v188, v87
	v_add_f32_e32 v87, v43, v96
	v_mul_f32_e32 v87, 0xbfb8aa3b, v87
	v_exp_f32_e32 v87, v87
	v_and_b32_e32 v97, 0xffff0000, v170
	v_lshlrev_b32_e32 v96, 16, v170
	v_pk_mov_b32 v[90:91], v[90:91], v[96:97] op_sel:[1,0]
	v_add_f32_e32 v87, 1.0, v87
	v_rcp_f32_e32 v87, v87
	v_pk_add_f32 v[90:91], v[90:91], v[96:97] neg_lo:[0,1] neg_hi:[0,1]
	v_pk_add_f32 v[84:85], v[84:85], v[92:93] neg_lo:[0,1] neg_hi:[0,1]
	v_pk_fma_f32 v[98:99], v[90:91], v[42:43], v[96:97] op_sel_hi:[1,0,1]
	v_pk_add_f32 v[90:91], v[86:87], -1.0 op_sel_hi:[1,0]
	v_pk_fma_f32 v[84:85], v[84:85], v[52:53], v[92:93] op_sel_hi:[1,0,1]
	v_pk_fma_f32 v[90:91], v[46:47], v[90:91], 1.0 op_sel_hi:[0,1,0]
	v_pk_mul_f32 v[90:91], v[98:99], v[90:91]
	s_nop 0
	v_mul_f32_e32 v190, v180, v90
	v_mul_f32_e32 v196, v103, v190
	v_mul_f32_e32 v190, v183, v91
	v_mul_f32_e32 v195, v103, v190
	v_sub_f32_e32 v190, v184, v188
	v_fma_f32 v188, v94, v95, v197

; __device__ __forceinline__ void rwkv_chunk_group(Frame& F, int bc, unsigned long long& tsub) {
;     ...
;             const float z = -(w0 + wl); const float sp = fmaxf(z, 0.f) + __logf(1.f + __expf(-fabsf(z)));
;     ...
;         wave_sum8(sq); wave_sum8(bq);
	ds_read_b32 v94, v125
	v_permlane32_swap_b32_e32 v101, v196
	v_permlane32_swap_b32_e32 v100, v195
	s_waitcnt lgkmcnt(0)
	v_add_f32_e32 v94, v45, v94
	v_max_f32_e64 v192, -v94, 0
	v_mul_f32_e64 v94, |v94|, s1
	v_exp_f32_e32 v94, v94
	v_add_f32_e32 v201, v101, v196
	v_add_f32_e32 v195, v100, v195
	v_add_f32_e32 v94, 1.0, v94

; __device__ __forceinline__ void rwkv_chunk_group(Frame& F, int bc, unsigned long long& tsub) {
;     ...
;             const float z = -(w0 + wl); const float sp = fmaxf(z, 0.f) + __logf(1.f + __expf(-fabsf(z)));
	s_nop 1


; __device__ __forceinline__ void rwkv_chunk_group(Frame& F, int bc, unsigned long long& tsub) {
;     ...
;             const float z = -(w0 + wl); const float sp = fmaxf(z, 0.f) + __logf(1.f + __expf(-fabsf(z)));
	v_log_f32_e32 v94, v94
	s_nop 0
	v_mul_f32_e32 v198, 0x3f317217, v94
	v_fma_f32 v198, v94, s9, -v198
	v_fmac_f32_e32 v198, 0x3377d1cf, v94
	v_fmac_f32_e32 v198, 0x3f317217, v94

; __device__ __forceinline__ void rwkv_chunk_group(Frame& F, int bc, unsigned long long& tsub) {
;     ...
;             const float z = -(w0 + wl); const float sp = fmaxf(z, 0.f) + __logf(1.f + __expf(-fabsf(z)));
	s_nop 1
	v_mov_b32_e32 v94, v198


; #define LAS __attribute__((address_space(3)))
; __device__ __forceinline__ void rwkv_chunk_group(Frame& F, int bc, unsigned long long& tsub) {
;     ...
;             const float r = cr + (pr - cr) * mur, k = ck + (pk - ck) * muk, v = cv + (pv - cv) * muv; pr = cr; pk = ck; pv = cv;
;             const float wl = *(const LAS float*)(L + L_WL + (t * 65 + ch) * 4), al = *(const LAS float*)(L + L_AL + (t * 65 + ch) * 4), gl = *(const LAS float*)(L + L_GL + (t * 65 + ch) * 4);
;             const float z = -(w0 + wl); const float sp = fmaxf(z, 0.f) + __logf(1.f + __expf(-fabsf(z)));
	v_lshlrev_b32_e32 v198, 16, v172
	v_pk_mov_b32 v[92:93], v[92:93], v[198:199] op_sel:[1,0]
	v_add_f32_e32 v94, v192, v94
	v_pk_add_f32 v[92:93], v[92:93], v[198:199] neg_lo:[0,1] neg_hi:[0,1]
	v_sub_f32_e32 v94, -0.5, v94
	v_pk_fma_f32 v[92:93], v[92:93], v[52:53], v[198:199] op_sel_hi:[1,0,1]

; #define LAS __attribute__((address_space(3)))
; __device__ __forceinline__ void rwkv_chunk_group(Frame& F, int bc, unsigned long long& tsub) {
;     ...
;             const float wl = *(const LAS float*)(L + L_WL + (t * 65 + ch) * 4), al = *(const LAS float*)(L + L_AL + (t * 65 + ch) * 4), gl = *(const LAS float*)(L + L_GL + (t * 65 + ch) * 4);
;             const float z = -(w0 + wl); const float sp = fmaxf(z, 0.f) + __logf(1.f + __expf(-fabsf(z)));
;             const float lgd = -__expf(-sp - 0.5f);
	ds_read_b32 v52, v126
	v_mul_f32_e32 v94, 0x3fb8aa3b, v94
	v_exp_f32_e32 v192, v94
	v_add_f32_e32 v94, v43, v191
	v_lshlrev_b32_e32 v191, 16, v163
	v_sub_f32_e32 v197, v197, v191
	v_fmac_f32_e32 v191, v197, v95


; #define LAS __attribute__((address_space(3)))
; __device__ __forceinline__ float sigmoidf_(float x) { return __builtin_amdgcn_rcpf(1.0f + __expf(-x)); }
; __device__ __forceinline__ void rwkv_chunk_group(Frame& F, int bc, unsigned long long& tsub) {
;     ...
;             const float wl = *(const LAS float*)(L + L_WL + (t * 65 + ch) * 4), al = *(const LAS float*)(L + L_AL + (t * 65 + ch) * 4), gl = *(const LAS float*)(L + L_GL + (t * 65 + ch) * 4);
;             const float z = -(w0 + wl); const float sp = fmaxf(z, 0.f) + __logf(1.f + __expf(-fabsf(z)));
;             const float lgd = -__expf(-sp - 0.5f);
;             const float ic = sigmoidf_(a0 + al);
	ds_read_b32 v95, v126 offset:16640
	ds_read_b32 v200, v126 offset:33280
	s_waitcnt lgkmcnt(2)
	v_add_f32_e32 v45, v45, v52
	v_max_f32_e64 v52, -v45, 0
	v_mul_f32_e64 v45, |v45|, s1
	v_exp_f32_e32 v45, v45
	s_waitcnt lgkmcnt(1)
	v_add_f32_e32 v43, v43, v95
	v_mul_f32_e32 v94, 0xbfb8aa3b, v94
	v_mul_f32_e32 v43, 0xbfb8aa3b, v43
	v_add_f32_e32 v45, 1.0, v45

; __device__ __forceinline__ float sigmoidf_(float x) { return __builtin_amdgcn_rcpf(1.0f + __expf(-x)); }
; __device__ __forceinline__ void rwkv_chunk_group(Frame& F, int bc, unsigned long long& tsub) {
;     ...
;             const float ic = sigmoidf_(a0 + al);
	v_exp_f32_e32 v94, v94
	v_exp_f32_e32 v43, v43


; __device__ __forceinline__ float sigmoidf_(float x) { return __builtin_amdgcn_rcpf(1.0f + __expf(-x)); }
; __device__ __forceinline__ void rwkv_chunk_group(Frame& F, int bc, unsigned long long& tsub) {
;     ...
;             const float z = -(w0 + wl); const float sp = fmaxf(z, 0.f) + __logf(1.f + __expf(-fabsf(z)));
;             const float lgd = -__expf(-sp - 0.5f);
;             const float ic = sigmoidf_(a0 + al);
	v_log_f32_e32 v45, v45
	v_add_f32_e32 v94, 1.0, v94
	v_add_f32_e32 v43, 1.0, v43
	v_rcp_f32_e32 v94, v94
	v_mul_f32_e32 v197, 0x3f317217, v45
	v_fma_f32 v197, v45, s9, -v197
	v_fmac_f32_e32 v197, 0x3377d1cf, v45
	v_fmac_f32_e32 v197, 0x3f317217, v45

; __device__ __forceinline__ float sigmoidf_(float x) { return __builtin_amdgcn_rcpf(1.0f + __expf(-x)); }
; __device__ __forceinline__ void rwkv_chunk_group(Frame& F, int bc, unsigned long long& tsub) {
;     ...
;             const float ic = sigmoidf_(a0 + al);
;             const float kv = k * k_k; const float kq = k * (1.f + (ic - 1.f) * k_a);
;             kkv[tt] = kv; icv[tt] = ic; sq[tt] = kv * kv; bq[tt] = r * kq * r_k;
;             rr[tt] = r; kp[tt] = kq; vv[tt] = v; run += lgd; ld[tt] = run; ggv[tt] = gl;
	v_rcp_f32_e32 v95, v43
	v_sub_f32_e32 v192, v190, v192
	v_mov_b32_e32 v45, v197


; #define GAS __attribute__((address_space(1)))
; #define LAS __attribute__((address_space(3)))
; __device__ __forceinline__ unsigned pk2(float lo, float hi) { f32x2_k v = {lo, hi}; bf16x2_k b = __builtin_convertvector(v, bf16x2_k); return __builtin_bit_cast(unsigned, b); }
; __device__ __forceinline__ void wave_sum8(float (&x)[8]) {
;     const float y0 = swap32_add(x[0], x[4]), y1 = swap32_add(x[1], x[5]), y2 = swap32_add(x[2], x[6]), y3 = swap32_add(x[3], x[7]);
;     float z0 = swap16_add(y0, y2), z1 = swap16_add(y1, y3);
;     z0 = dpp_add(z0, 0); z1 = dpp_add(z1, 0); z0 = dpp_add(z0, 1); z1 = dpp_add(z1, 1); z0 = dpp_add(z0, 2); z1 = dpp_add(z1, 2); z0 = dpp_add(z0, 3); z1 = dpp_add(z1, 3);
;     const int i0 = __builtin_bit_cast(int, z0), i1 = __builtin_bit_cast(int, z1);
;     x[0] = __builtin_bit_cast(float, __builtin_amdgcn_readlane(i0, 0));  x[2] = __builtin_bit_cast(float, __builtin_amdgcn_readlane(i0, 16));
;     x[4] = __builtin_bit_cast(float, __builtin_amdgcn_readlane(i0, 32)); x[6] = __builtin_bit_cast(float, __builtin_amdgcn_readlane(i0, 48));
;     x[1] = __builtin_bit_cast(float, __builtin_amdgcn_readlane(i1, 0));  x[3] = __builtin_bit_cast(float, __builtin_amdgcn_readlane(i1, 16));
;     x[5] = __builtin_bit_cast(float, __builtin_amdgcn_readlane(i1, 32)); x[7] = __builtin_bit_cast(float, __builtin_amdgcn_readlane(i1, 48));
; }
; __device__ __forceinline__ void rwkv_chunk_group(Frame& F, int bc, unsigned long long& tsub) {
;     ...
;         wave_sum8(sq); wave_sum8(bq);
; #pragma unroll
;         for (int tt = 0; tt < 8; ++tt) { const float kn = kkv[tt] * __builtin_amdgcn_rsqf(fmaxf(sq[tt], 1e-24f));
;             aa[tt] = -kn; bb[tt] = kn * icv[tt]; vbv[tt] = bq[tt] * vv[tt]; }
;         *(LAS float*)(L + L_GT + (w * 64 + ch) * 4) = run;
;         *(GAS v4u*)(VBp + ch * 64 + tb) = (v4u){pk2(vbv[0], vbv[1]), pk2(vbv[2], vbv[3]), pk2(vbv[4], vbv[5]), pk2(vbv[6], vbv[7])};
;         *(GAS v4u*)(Gp + ch * 64 + tb) = (v4u){pk2(ggv[0], ggv[1]), pk2(ggv[2], ggv[3]), pk2(ggv[4], ggv[5]), pk2(ggv[6], ggv[7])};
;         if (hh + 1 < RW_H) {
;             const bool has = (c * CH + tb > 0);
; #pragma unroll
;             for (int tt = 0; tt < 9; ++tt) { const size_t off = (size_t)(row0 + tb + tt - 1) * PRW + hnext * 64 + ch;
;                 if (tt > 0 || has) { raw[tt][0] = P[off]; raw[tt][1] = P[off + 512]; raw[tt][2] = P[off + 1024]; } }
	v_add_f32_e32 v45, v52, v45
	v_sub_f32_e32 v45, -0.5, v45
	v_mul_f32_e32 v45, 0x3fb8aa3b, v45
	v_exp_f32_e32 v45, v45
	s_nop 0
	v_pk_mul_f32 v[100:101], v[80:81], v[44:45] op_sel_hi:[1,0]
	v_pk_mul_f32 v[80:81], v[98:99], v[44:45] op_sel_hi:[1,0]
	v_pk_mul_f32 v[196:197], v[100:101], v[100:101]
	v_pk_mul_f32 v[98:99], v[80:81], v[80:81]
	v_sub_f32_e32 v52, v192, v45
	s_nop 0
	v_permlane32_swap_b32_e32 v196, v98
	v_permlane32_swap_b32_e32 v197, v99
	v_add_f32_e32 v196, v196, v98
	v_add_f32_e32 v197, v197, v99
	v_lshlrev_b32_e32 v98, 16, v165
	v_and_b32_e32 v99, 0xffff0000, v165
	v_pk_mov_b32 v[96:97], v[96:97], v[98:99] op_sel:[1,0]
	v_pk_mul_f32 v[88:89], v[88:89], v[44:45] op_sel_hi:[1,0]
	v_pk_add_f32 v[96:97], v[96:97], v[98:99] neg_lo:[0,1] neg_hi:[0,1]
	v_pk_mul_f32 v[198:199], v[88:89], v[88:89]
	v_pk_fma_f32 v[42:43], v[96:97], v[42:43], v[98:99] op_sel_hi:[1,0,1]
	v_pk_add_f32 v[98:99], v[94:95], -1.0 op_sel_hi:[1,0]
	v_pk_mul_f32 v[44:45], v[42:43], v[44:45] op_sel_hi:[1,0]
	v_pk_fma_f32 v[98:99], v[46:47], v[98:99], 1.0 op_sel_hi:[0,1,0]
	v_pk_mul_f32 v[42:43], v[42:43], v[98:99]
	v_pk_mul_f32 v[96:97], v[44:45], v[44:45]
	v_mul_f32_e32 v46, v188, v42
	v_mul_f32_e32 v46, v103, v46
	s_nop 1
	v_permlane32_swap_b32_e32 v187, v46
	v_add_f32_e32 v46, v187, v46
	v_mul_f32_e32 v98, v191, v43
	s_nop 0
	v_permlane16_swap_b32_e32 v201, v46
	v_mul_f32_e32 v98, v103, v98
	v_add_f32_e32 v46, v201, v46
	s_nop 0
	v_permlane32_swap_b32_e32 v186, v98
	v_add_f32_dpp v46, v46, v46 quad_perm:[1,0,3,2] row_mask:0xf bank_mask:0xf bound_ctrl:1
	v_add_f32_e32 v98, v186, v98
	s_nop 1
	v_permlane16_swap_b32_e32 v195, v98
	v_add_f32_dpp v46, v46, v46 quad_perm:[2,3,0,1] row_mask:0xf bank_mask:0xf bound_ctrl:1
	v_add_f32_e32 v98, v195, v98
	v_permlane32_swap_b32_e32 v198, v96
	v_add_f32_dpp v46, v46, v46 row_half_mirror row_mask:0xf bank_mask:0xf bound_ctrl:1
	v_permlane32_swap_b32_e32 v199, v97
	s_nop 0
	v_add_f32_dpp v46, v46, v46 row_mirror row_mask:0xf bank_mask:0xf bound_ctrl:1
	v_add_f32_dpp v98, v98, v98 quad_perm:[1,0,3,2] row_mask:0xf bank_mask:0xf bound_ctrl:1
	v_readlane_b32 s14, v46, 0
	v_readlane_b32 s64, v46, 16
	v_readlane_b32 s72, v46, 32
	v_readlane_b32 s96, v46, 48
	v_add_f32_e32 v46, v198, v96
	v_add_f32_e32 v96, v199, v97
	v_add_f32_dpp v98, v98, v98 quad_perm:[2,3,0,1] row_mask:0xf bank_mask:0xf bound_ctrl:1
	v_permlane16_swap_b32_e32 v196, v46
	v_permlane16_swap_b32_e32 v197, v96
	v_add_f32_dpp v98, v98, v98 row_half_mirror row_mask:0xf bank_mask:0xf bound_ctrl:1
	v_add_f32_e32 v46, v196, v46
	v_add_f32_e32 v96, v197, v96
	v_add_f32_dpp v98, v98, v98 row_mirror row_mask:0xf bank_mask:0xf bound_ctrl:1
	v_add_f32_dpp v46, v46, v46 quad_perm:[1,0,3,2] row_mask:0xf bank_mask:0xf bound_ctrl:1
	v_add_f32_dpp v96, v96, v96 quad_perm:[1,0,3,2] row_mask:0xf bank_mask:0xf bound_ctrl:1
	v_readlane_b32 s73, v98, 32
	v_add_f32_dpp v46, v46, v46 quad_perm:[2,3,0,1] row_mask:0xf bank_mask:0xf bound_ctrl:1
	v_add_f32_dpp v96, v96, v96 quad_perm:[2,3,0,1] row_mask:0xf bank_mask:0xf bound_ctrl:1
	v_readlane_b32 s15, v98, 0
	v_readlane_b32 s65, v98, 16
	v_readlane_b32 s97, v98, 48
	v_add_f32_dpp v46, v46, v46 row_half_mirror row_mask:0xf bank_mask:0xf bound_ctrl:1
	v_add_f32_dpp v96, v96, v96 row_half_mirror row_mask:0xf bank_mask:0xf bound_ctrl:1
	v_pk_mul_f32 v[196:197], v[84:85], s[72:73]
	s_lshl_b64 s[72:73], s[66:67], 13
	v_pk_mul_f32 v[98:99], v[36:37], s[14:15]
	v_pk_mul_f32 v[186:187], v[76:77], s[64:65]
	v_add_f32_dpp v46, v46, v46 row_mirror row_mask:0xf bank_mask:0xf bound_ctrl:1
	v_add_f32_dpp v96, v96, v96 row_mirror row_mask:0xf bank_mask:0xf bound_ctrl:1
	v_pk_mul_f32 v[198:199], v[92:93], s[96:97]
	v_readlane_b32 s15, v254, 39
	s_cmp_eq_u32 s68, 7
	v_readlane_b32 s93, v46, 0
	v_readlane_b32 s71, v46, 16
	v_readlane_b32 s69, v46, 32
	v_readlane_b32 s64, v46, 48
	v_readlane_b32 s14, v96, 0
	v_readlane_b32 s77, v96, 16
	v_readlane_b32 s70, v96, 32
	v_readlane_b32 s65, v96, 48
	v_add_u32_e32 v46, s15, v105
	v_cvt_pk_bf16_f32 v96, v98, v99
	v_cvt_pk_bf16_f32 v97, v186, v187
	v_cvt_pk_bf16_f32 v98, v196, v197
	v_cvt_pk_bf16_f32 v99, v198, v199
	v_lshl_add_u64 v[186:187], v[62:63], 0, s[72:73]
	s_cselect_b64 s[96:97], -1, 0
	ds_write_b32 v46, v52
	global_store_dwordx4 v[186:187], v[96:99], off
	s_and_b64 vcc, exec, s[96:97]
	s_nop 0
	v_cvt_pk_bf16_f32 v96, v47, v177
	v_cvt_pk_bf16_f32 v97, v182, v185
	v_cvt_pk_bf16_f32 v98, v189, v193
	s_waitcnt lgkmcnt(1)
	v_cvt_pk_bf16_f32 v99, v194, v200
	v_lshl_add_u64 v[46:47], v[64:65], 0, s[72:73]
	global_store_dwordx4 v[46:47], v[96:99], off
	s_cbranch_vccnz .LBB0_1416
	v_readlane_b32 s72, v254, 60
	s_lshl_b32 s94, s13, 7
	v_readlane_b32 s73, v254, 61
	v_lshl_add_u64 v[46:47], v[56:57], 0, s[94:95]
	s_andn2_b64 vcc, exec, s[72:73]
	s_cbranch_vccnz .LBB0_1415
	v_readlane_b32 s72, v254, 62
	v_readlane_b32 s73, v254, 63
	s_nop 1
	v_lshl_add_u64 v[96:97], v[46:47], 0, s[72:73]
	global_load_ushort v153, v[96:97], off
	global_load_ushort v202, v[96:97], off offset:1024
	global_load_ushort v215, v[96:97], off offset:2048
